# attention tile loop: the accumulator tile's -m fill (9 VALU moves) issued at the end of the previous segment instead of at the head of its own (segment opens with K reads and the first MFMA)
# speedup vs baseline: 1.0002x; 1.0002x over previous
.LBB0_422:
	s_lshl_b32 s0, s39, 10
	s_and_b32 s6, s0, 0x800000
	s_lshl_b32 s0, s43, 1
	s_and_b32 s66, s0, 0x300
	s_lshl_b32 s0, s64, 11
	s_lshl_b32 s1, s64, 4
	s_and_b32 s0, s0, 0x2000
	s_and_b32 s1, s1, 0xffffff80
	s_add_i32 s1, s0, s1
	v_or_b32_e32 v171, s1, v170
	v_or_b32_e32 v0, v171, v169
	v_ashrrev_i32_e32 v1, 31, v0
	s_lshl_b32 s1, s64, 7
	v_lshlrev_b64 v[0:1], 10, v[0:1]
	s_and_b32 s65, s1, 0x180
	v_lshl_add_u64 v[0:1], s[86:87], 0, v[0:1]
	s_lshl_b32 s4, s65, 1
	s_mov_b32 s5, s7
	v_lshl_add_u64 v[0:1], v[0:1], 0, s[4:5]
	s_lshl_b32 s5, s0, 10
	s_add_u32 s0, s33, s5
	s_addc_u32 s1, s34, 0
	s_add_u32 s0, s0, s4
	v_mov_b32_e32 v174, v168
	v_lshl_add_u64 v[0:1], v[160:161], 1, v[0:1]
	s_addc_u32 s1, s1, 0
	v_lshl_add_u64 v[0:1], v[0:1], 0, v[162:163]
	v_ashrrev_i32_e32 v16, 4, v174
	s_add_u32 s5, s35, s5
	v_lshlrev_b32_e32 v20, 3, v174
	v_add_u32_e32 v18, 32, v16
	s_addc_u32 s16, s38, 0
	global_load_dwordx4 v[124:127], v[0:1], off
	global_load_dwordx4 v[120:123], v[0:1], off offset:32
	global_load_dwordx4 v[116:119], v[0:1], off offset:64
	global_load_dwordx4 v[112:115], v[0:1], off offset:96
	v_and_b32_e32 v0, 0x78, v20
	v_ashrrev_i32_e32 v17, 31, v16
	v_ashrrev_i32_e32 v19, 31, v18
	s_add_u32 s4, s5, s4
	v_lshlrev_b32_e32 v21, 1, v0
	v_lshlrev_b64 v[48:49], 10, v[16:17]
	v_lshlrev_b64 v[12:13], 10, v[18:19]
	s_addc_u32 s5, s16, 0
	v_or_b32_e32 v50, v48, v21
	v_mov_b32_e32 v51, v49
	v_or_b32_e32 v12, v12, v21
	v_lshl_add_u64 v[0:1], s[4:5], 0, v[50:51]
	v_lshl_add_u64 v[4:5], s[4:5], 0, v[12:13]
	s_barrier
	global_load_dwordx4 v[0:3], v[0:1], off
	s_nop 0
	global_load_dwordx4 v[4:7], v[4:5], off
	v_lshl_add_u64 v[8:9], s[0:1], 0, v[50:51]
	global_load_dwordx4 v[8:11], v[8:9], off
	v_lshl_add_u64 v[12:13], s[0:1], 0, v[12:13]
	global_load_dwordx4 v[12:15], v[12:13], off
	v_and_b32_e32 v22, 0xfffff0, v16
	v_lshlrev_b32_e32 v23, 1, v16
	v_lshrrev_b32_e32 v24, 1, v16
	v_and_b32_e32 v25, 3, v16
	v_and_or_b32 v22, v23, 8, v22
	v_and_or_b32 v23, v24, 4, v25
	v_and_b32_e32 v24, 0xfffff0, v18
	v_lshlrev_b32_e32 v25, 1, v18
	v_and_b32_e32 v17, 0x70, v174
	v_bfe_u32 v20, v20, 5, 2
	v_lshlrev_b32_e32 v16, 8, v16
	v_lshrrev_b32_e32 v22, 1, v22
	v_and_or_b32 v24, v25, 8, v24
	v_bitop3_b32 v183, v21, v16, v17 bitop3:0xde
	v_or_b32_e32 v16, v22, v20
	v_lshrrev_b32_e32 v22, 1, v24
	v_lshlrev_b32_e32 v23, 6, v23
	v_and_b32_e32 v26, 48, v21
	v_lshlrev_b32_e32 v16, 9, v16
	v_or_b32_e32 v20, v22, v20
	v_or3_b32 v184, v16, v23, v26
	v_lshlrev_b32_e32 v16, 9, v20
	v_bfe_u32 v172, v174, 5, 1
	v_ashrrev_i32_e32 v175, 8, v174
	v_lshlrev_b32_e32 v52, 4, v174
	v_or3_b32 v186, v16, v23, v26
	v_add_u32_e32 v84, 16, v184
	v_and_b32_e32 v173, 31, v174
	v_lshlrev_b32_e32 v19, 7, v175
	v_add_u32_e32 v24, 16, v183
	v_add_u32_e32 v85, 16, v186
	s_waitcnt vmcnt(0)
	v_lshlrev_b32_e32 v176, 4, v172
	v_lshlrev_b32_e32 v190, 8, v173
	v_and_b32_e32 v86, 63, v174
	v_lshl_add_u64 v[60:61], v[50:51], 0, s[14:15]
	v_lshl_add_u64 v[64:65], v[50:51], 0, s[36:37]
	v_lshl_add_u64 v[56:57], s[4:5], 0, v[64:65]
	v_lshl_add_u64 v[64:65], s[0:1], 0, v[64:65]
	s_cmp_lg_u32 16, -1
	s_cselect_b32 s16, 16, 0
	s_mov_b32 s17, s7
	s_mov_b32 s18, s7
	s_mov_b32 s19, s7
	s_mov_b32 s20, s7
	s_waitcnt vmcnt(3)
	ds_write_b128 v84, v[0:3]
	s_waitcnt vmcnt(2)
	ds_write_b128 v85, v[4:7]
	s_waitcnt vmcnt(1)
	ds_write_b128 v24, v[8:11] offset:49152
	v_and_b32_e32 v8, 0x70, v52
	v_lshlrev_b32_e32 v0, 8, v18
	v_bitop3_b32 v182, v176, v8, v19 bitop3:0x36
	v_bitop3_b32 v188, v21, v0, v17 bitop3:0xde
	v_add_u32_e32 v185, v182, v190
	v_add_u32_e32 v0, 16, v188
	v_add_u32_e32 v4, 16, v185
	s_waitcnt vmcnt(0)
	ds_write_b128 v0, v[12:15] offset:49152
	s_waitcnt lgkmcnt(0)
	s_barrier
	ds_read_b128 v[0:3], v4 offset:49152
	ds_read_b128 v[4:7], v4 offset:57344
	v_or_b32_e32 v9, v176, v19
	v_bitop3_b32 v187, v9, v8, 32 bitop3:0x36
	v_add_u32_e32 v189, v187, v190
	s_waitcnt lgkmcnt(0)
	v_mfma_f32_32x32x16_bf16 v[16:31], v[4:7], v[124:127], 0
	v_add_u32_e32 v4, 16, v189
	v_bitop3_b32 v193, v9, v8, s3 bitop3:0x36
	v_bitop3_b32 v191, v9, v8, 64 bitop3:0x36
	v_add_u32_e32 v194, v193, v190
	v_add_u32_e32 v192, v191, v190
	v_add_u32_e32 v8, 16, v194
	v_and_b32_e32 v5, 0x3fffffc0, v174
	v_mfma_f32_32x32x16_bf16 v[32:47], v[0:3], v[124:127], 0
	ds_read_b128 v[0:3], v4 offset:49152
	v_and_b32_e32 v11, 0xc0, v52
	v_add_u32_e32 v13, 16, v192
	ds_read_b128 v[52:55], v8 offset:57344
	v_lshl_add_u32 v177, v5, 2, s50
	ds_read_b128 v[4:7], v4 offset:57344
	v_lshlrev_b32_e32 v10, 3, v86
	s_waitcnt lgkmcnt(2)
	v_mfma_f32_32x32x16_bf16 v[32:47], v[0:3], v[120:123], v[32:47]
	v_lshlrev_b32_e32 v0, 1, v174
	v_and_b32_e32 v12, 32, v0
	ds_read_b128 v[0:3], v13 offset:49152
	v_and_or_b32 v11, v10, 24, v11
	s_mov_b32 s21, s7
	s_mov_b32 s22, s7
	s_mov_b32 s23, s7
	s_waitcnt lgkmcnt(0)
	v_mfma_f32_32x32x16_bf16 v[32:47], v[0:3], v[116:119], v[32:47]
	ds_read_b128 v[0:3], v8 offset:49152
	s_mov_b32 s24, s7
	s_mov_b32 s25, s7
	s_mov_b32 s26, s7
	s_mov_b32 s27, s7
	s_mov_b32 s28, s7
	s_mov_b32 s29, s7
	v_mfma_f32_32x32x16_bf16 v[16:31], v[4:7], v[120:123], v[16:31]
	v_and_b32_e32 v4, 0x100, v10
	v_lshlrev_b32_e32 v4, 3, v4
	v_or3_b32 v178, v11, v12, v4
	ds_read_b128 v[4:7], v13 offset:57344
	v_add_u32_e32 v181, s16, v178
	s_mov_b32 s16, s7
	s_mov_b32 s30, s7
	s_mov_b32 s31, s7
	s_waitcnt lgkmcnt(0)
	v_mfma_f32_32x32x16_bf16 v[16:31], v[4:7], v[116:119], v[16:31]
	v_lshl_add_u32 v179, v173, 2, v177
	v_mov_b32_e32 v196, 1.0
	v_mov_b32_e32 v180, 0
	v_mfma_f32_32x32x16_bf16 v[32:47], v[0:3], v[112:115], v[32:47]
	v_mov_b64_e32 v[0:1], s[16:17]
	v_mov_b64_e32 v[14:15], s[30:31]
	v_mov_b64_e32 v[2:3], s[18:19]
	v_mov_b64_e32 v[4:5], s[20:21]
	v_mov_b64_e32 v[6:7], s[22:23]
	v_mov_b64_e32 v[8:9], s[24:25]
	v_mov_b64_e32 v[10:11], s[26:27]
	v_mfma_f32_32x32x16_bf16 v[16:31], v[52:55], v[112:115], v[16:31]
	s_nop 3
	v_max_f32_e32 v52, v33, v33
	v_max_f32_e32 v53, v32, v32
	v_max_f32_e32 v52, v53, v52
	v_max3_f32 v52, v52, v34, v35
	v_max3_f32 v52, v52, v36, v37
	v_max3_f32 v52, v52, v38, v39
	v_max3_f32 v52, v52, v40, v41
	v_max3_f32 v52, v52, v42, v43
	v_max3_f32 v52, v52, v44, v45
	v_max3_f32 v66, v52, v46, v47
	v_lshl_add_u64 v[52:53], s[4:5], 0, v[60:61]
	v_lshl_add_u64 v[60:61], s[0:1], 0, v[60:61]
	global_load_dwordx4 v[52:55], v[52:53], off
	s_nop 0
	global_load_dwordx4 v[56:59], v[56:57], off
	v_mov_b64_e32 v[12:13], s[28:29]
	global_load_dwordx4 v[60:63], v[60:61], off
	s_mov_b32 s19, 1
	global_load_dwordx4 v[80:83], v[64:65], off
	v_max3_f32 v64, v66, v16, v17
	v_max3_f32 v64, v64, v18, v19
	v_max3_f32 v64, v64, v20, v21
	v_max3_f32 v64, v64, v22, v23
	v_max3_f32 v64, v64, v24, v25
	v_max3_f32 v64, v64, v26, v27
	v_max3_f32 v64, v64, v28, v29
	v_max3_f32 v70, v64, v30, v31
	v_lshl_add_u64 v[64:65], v[50:51], 0, s[40:41]
	v_lshl_add_u64 v[66:67], s[0:1], 0, v[64:65]
	v_lshl_add_u64 v[50:51], v[50:51], 0, s[44:45]
	v_lshl_add_u64 v[64:65], s[4:5], 0, v[64:65]
	v_lshl_add_u64 v[68:69], s[0:1], 0, v[50:51]
	global_load_dwordx4 v[136:139], v[66:67], off
	global_load_dwordx4 v[128:131], v[68:69], off
	v_lshl_add_u64 v[50:51], s[4:5], 0, v[50:51]
	global_load_dwordx4 v[140:143], v[64:65], off
	global_load_dwordx4 v[132:135], v[50:51], off
	v_mov_b32_e32 v71, v70
	s_nop 1
	v_permlane32_swap_b32_e32 v70, v71
	v_max_f32_e32 v50, v71, v71
	v_max_f32_e32 v51, v70, v70
	v_max_f32_e32 v50, v51, v50
	v_sub_f32_e32 v64, v16, v50
	v_add_u32_e32 v16, s58, v183
	v_sub_f32_e32 v32, v32, v50
	v_sub_f32_e32 v33, v33, v50
	v_sub_f32_e32 v34, v34, v50
	v_sub_f32_e32 v35, v35, v50
	v_sub_f32_e32 v36, v36, v50
	v_sub_f32_e32 v37, v37, v50
	v_sub_f32_e32 v38, v38, v50
	v_sub_f32_e32 v39, v39, v50
	v_sub_f32_e32 v40, v40, v50
	v_sub_f32_e32 v41, v41, v50
	v_sub_f32_e32 v42, v42, v50
	v_sub_f32_e32 v43, v43, v50
	v_sub_f32_e32 v44, v44, v50
	v_sub_f32_e32 v45, v45, v50
	v_sub_f32_e32 v46, v46, v50
	v_sub_f32_e32 v47, v47, v50
	v_sub_f32_e32 v66, v18, v50
	s_waitcnt vmcnt(4)
	s_waitcnt vmcnt(7)
	ds_write_b128 v84, v[52:55] offset:16384
	s_waitcnt vmcnt(6)
	ds_write_b128 v85, v[56:59] offset:16384
	v_and_b32_e32 v18, 15, v174
	s_waitcnt vmcnt(5)
	ds_write_b128 v16, v[60:63]
	v_add_u32_e32 v16, s58, v188
	v_sub_f32_e32 v65, v17, v50
	v_exp_f32_e32 v152, v32
	v_exp_f32_e32 v153, v33
	v_exp_f32_e32 v154, v34
	v_exp_f32_e32 v155, v35
	v_exp_f32_e32 v156, v36
	v_exp_f32_e32 v157, v37
	v_exp_f32_e32 v158, v38
	v_exp_f32_e32 v159, v39
	v_exp_f32_e32 v144, v40
	v_exp_f32_e32 v145, v41
	v_exp_f32_e32 v146, v42
	v_exp_f32_e32 v147, v43
	v_exp_f32_e32 v148, v44
	v_exp_f32_e32 v149, v45
	v_exp_f32_e32 v150, v46
	v_exp_f32_e32 v151, v47
	s_waitcnt vmcnt(4)
	ds_write_b128 v16, v[80:83]
	v_lshl_add_u64 v[16:17], s[6:7], 0, v[48:49]
	v_lshlrev_b32_e32 v18, 4, v18
	v_or3_b32 v16, v16, s66, v18
	v_add_f32_e32 v195, 0, v50
	v_sub_f32_e32 v79, v31, v50
	v_sub_f32_e32 v78, v30, v50
	v_sub_f32_e32 v77, v29, v50
	v_sub_f32_e32 v76, v28, v50
	v_sub_f32_e32 v75, v27, v50
	v_sub_f32_e32 v74, v26, v50
	v_sub_f32_e32 v73, v25, v50
	v_sub_f32_e32 v72, v24, v50
	v_sub_f32_e32 v71, v23, v50
	v_sub_f32_e32 v70, v22, v50
	v_sub_f32_e32 v69, v21, v50
	v_sub_f32_e32 v68, v20, v50
	v_sub_f32_e32 v67, v19, v50
	v_lshl_add_u64 v[166:167], s[12:13], 0, v[16:17]
	v_mov_b64_e32 v[62:63], v[14:15]
	v_mov_b64_e32 v[46:47], v[14:15]
	v_mov_b64_e32 v[30:31], v[14:15]
	v_cmp_gt_u32_e64 s[0:1], 32, v86
	v_mov_b64_e32 v[60:61], v[12:13]
	v_mov_b64_e32 v[58:59], v[10:11]
	v_mov_b64_e32 v[56:57], v[8:9]
	v_mov_b64_e32 v[54:55], v[6:7]
	v_mov_b64_e32 v[52:53], v[4:5]
	v_mov_b64_e32 v[50:51], v[2:3]
	v_mov_b64_e32 v[48:49], v[0:1]
	v_mov_b64_e32 v[44:45], v[12:13]
	v_mov_b64_e32 v[42:43], v[10:11]
	v_mov_b64_e32 v[40:41], v[8:9]
	v_mov_b64_e32 v[38:39], v[6:7]
	v_mov_b64_e32 v[36:37], v[4:5]
	v_mov_b64_e32 v[34:35], v[2:3]
	v_mov_b64_e32 v[32:33], v[0:1]
	v_mov_b64_e32 v[28:29], v[12:13]
	v_mov_b64_e32 v[26:27], v[10:11]
	v_mov_b64_e32 v[24:25], v[8:9]
	v_mov_b64_e32 v[22:23], v[6:7]
	v_mov_b64_e32 v[20:21], v[4:5]
	v_mov_b64_e32 v[18:19], v[2:3]
	v_mov_b64_e32 v[16:17], v[0:1]
	s_mov_b32 s6, 1
	s_mov_b32 s18, 0
	s_waitcnt lgkmcnt(0)
	s_barrier
	v_add_co_u32_e32 v242, vcc, s61, v166
	s_nop 1
	v_addc_co_u32_e32 v243, vcc, -1, v167, vcc
	s_nop 0
	v_readfirstlane_b32 s98, v242
	v_readfirstlane_b32 s99, v243
	s_nop 1
	v_subrev_u32_e32 v242, s98, v242
	v_add_u32_e32 v243, 0x8000, v242
	v_add_u32_e32 v244, 0x1000000, v242
	v_add_u32_e32 v245, 0x1008000, v242
	v_xor_b32_e32 v80, 0x80000000, v195
	v_mov_b32_e32 v81, v80
	v_mov_b64_e32 v[82:83], v[80:81]
	v_mov_b64_e32 v[84:85], v[80:81]
	v_mov_b64_e32 v[86:87], v[80:81]
	v_mov_b64_e32 v[88:89], v[80:81]
	v_mov_b64_e32 v[90:91], v[80:81]
	v_mov_b64_e32 v[92:93], v[80:81]
	v_mov_b64_e32 v[94:95], v[80:81]
.LBB0_423:
	s_lshl_b32 s16, s19, 14
	s_add_i32 s4, s16, 16
	v_add_u32_e32 v96, s4, v185
	ds_read_b128 v[198:201], v96 offset:49152
	ds_read_b128 v[202:205], v96 offset:57344
	v_exp_f32_e32 v221, v64
	s_waitcnt lgkmcnt(1)
	v_mfma_f32_32x32x16_bf16 v[96:111], v[198:201], v[124:127], v[80:95]
	v_add_f32_e32 v64, v153, v152
	v_add_f32_e32 v64, v154, v64
	v_add_u32_e32 v197, s4, v189
	v_add_f32_e32 v64, v155, v64
	v_add_f32_e32 v64, v156, v64
	v_add_f32_e32 v64, v157, v64
	v_add_f32_e32 v64, v158, v64
	s_waitcnt lgkmcnt(0)
	v_mfma_f32_32x32x16_bf16 v[80:95], v[202:205], v[124:127], v[80:95]
	ds_read_b128 v[198:201], v197 offset:49152
	ds_read_b128 v[202:205], v197 offset:57344
	v_add_f32_e32 v64, v159, v64
	v_add_f32_e32 v64, v144, v64
	v_add_f32_e32 v64, v145, v64
	v_add_f32_e32 v64, v146, v64
	v_add_u32_e32 v197, s4, v192
	v_add_f32_e32 v64, v147, v64
	s_waitcnt lgkmcnt(1)
	v_mfma_f32_32x32x16_bf16 v[96:111], v[198:201], v[120:123], v[96:111]
	ds_read_b128 v[198:201], v197 offset:49152
	ds_read_b128 v[206:209], v197 offset:57344
	v_add_f32_e32 v64, v148, v64
	v_exp_f32_e32 v222, v65
	v_add_f32_e32 v64, v149, v64
	v_exp_f32_e32 v223, v66
	v_add_f32_e32 v64, v150, v64
	v_exp_f32_e32 v224, v67
	s_waitcnt lgkmcnt(2)
	v_mfma_f32_32x32x16_bf16 v[80:95], v[202:205], v[120:123], v[80:95]
	v_add_f32_e32 v64, v151, v64
	v_add_f32_e32 v64, v221, v64
	v_add_f32_e32 v64, v222, v64
	v_add_f32_e32 v64, v223, v64
	v_exp_f32_e32 v71, v71
	v_add_f32_e32 v64, v224, v64
	v_add_u32_e32 v197, s4, v194
	s_waitcnt lgkmcnt(1)
	v_mfma_f32_32x32x16_bf16 v[96:111], v[198:201], v[116:119], v[96:111]
	v_exp_f32_e32 v199, v68
	v_exp_f32_e32 v200, v69
	v_exp_f32_e32 v201, v70
	v_exp_f32_e32 v225, v72
	v_add_f32_e32 v64, v199, v64
	ds_read_b128 v[202:205], v197 offset:49152
	ds_read_b128 v[210:213], v197 offset:57344
	v_exp_f32_e32 v226, v73
	s_waitcnt lgkmcnt(2)
	v_mfma_f32_32x32x16_bf16 v[80:95], v[206:209], v[116:119], v[80:95]
	v_add_f32_e32 v64, v200, v64
	v_exp_f32_e32 v227, v74
	v_add_f32_e32 v64, v201, v64
	v_exp_f32_e32 v206, v75
	v_add_f32_e32 v64, v71, v64
	v_exp_f32_e32 v207, v76
	v_add_f32_e32 v64, v225, v64
	v_exp_f32_e32 v208, v77
	v_add_f32_e32 v64, v226, v64
	v_exp_f32_e32 v209, v78
	s_waitcnt lgkmcnt(1)
	v_mfma_f32_32x32x16_bf16 v[96:111], v[202:205], v[112:115], v[96:111]
	v_add_f32_e32 v64, v227, v64
	v_exp_f32_e32 v79, v79
	v_add_f32_e32 v64, v206, v64
	v_add_f32_e32 v64, v207, v64
	v_add_f32_e32 v64, v208, v64
	v_add_f32_e32 v64, v209, v64
	v_add_f32_e32 v197, v79, v64
	s_waitcnt lgkmcnt(0)
	v_mfma_f32_32x32x16_bf16 v[80:95], v[210:213], v[112:115], v[80:95]
	v_cvt_pk_bf16_f32 v64, v152, v153
	v_cvt_pk_bf16_f32 v65, v154, v155
	v_cvt_pk_bf16_f32 v66, v156, v157
	v_cvt_pk_bf16_f32 v67, v158, v159
	v_cvt_pk_bf16_f32 v72, v144, v145
	v_cvt_pk_bf16_f32 v73, v146, v147
	v_cvt_pk_bf16_f32 v74, v148, v149
	v_cvt_pk_bf16_f32 v75, v150, v151
	v_cvt_pk_bf16_f32 v68, v221, v222
	v_cvt_pk_bf16_f32 v69, v223, v224
	v_cvt_pk_bf16_f32 v70, v199, v200
	v_cvt_pk_bf16_f32 v71, v201, v71
	v_cvt_pk_bf16_f32 v76, v225, v226
	v_cvt_pk_bf16_f32 v77, v227, v206
	v_cvt_pk_bf16_f32 v78, v207, v208
	v_cvt_pk_bf16_f32 v79, v209, v79
	global_load_dwordx4 v[144:147], v244, s[98:99]
	global_load_dwordx4 v[148:151], v245, s[98:99]
	global_load_dwordx4 v[152:155], v242, s[98:99]
	global_load_dwordx4 v[156:159], v243, s[98:99]
	s_add_u32 s98, s98, 0x10000
	s_addc_u32 s99, s99, 0
	v_lshl_add_u32 v199, s18, 14, v181
	ds_read_b64_tr_b16 v[200:201], v199 offset:0
	ds_read_b64_tr_b16 v[202:203], v199 offset:0x100
	ds_read_b64_tr_b16 v[204:205], v199 offset:0x1000
	ds_read_b64_tr_b16 v[206:207], v199 offset:0x1100
	ds_read_b64_tr_b16 v[208:209], v199 offset:0x2000
	ds_read_b64_tr_b16 v[210:211], v199 offset:0x2100
	ds_read_b64_tr_b16 v[222:223], v199 offset:0x3000
	ds_read_b64_tr_b16 v[224:225], v199 offset:0x3100
	s_waitcnt lgkmcnt(6)
	v_mfma_f32_32x32x16_bf16 v[0:15], v[64:67], v[200:203], v[0:15]
	v_max_f32_e32 v200, v96, v97
	v_max3_f32 v200, v200, v98, v99
	v_max3_f32 v200, v200, v100, v101
	v_max3_f32 v200, v200, v102, v103
	v_max3_f32 v200, v200, v104, v105
	s_waitcnt lgkmcnt(4)
	v_mfma_f32_32x32x16_bf16 v[0:15], v[72:75], v[204:207], v[0:15]
	v_max3_f32 v200, v200, v106, v107
	v_max3_f32 v202, v200, v108, v109
	ds_read_b64_tr_b16 v[200:201], v199 offset:0x200
	v_max3_f32 v212, v202, v110, v111
	ds_read_b64_tr_b16 v[202:203], v199 offset:0x300
	ds_read_b64_tr_b16 v[204:205], v199 offset:0x1200
	ds_read_b64_tr_b16 v[206:207], v199 offset:0x1300
	s_waitcnt lgkmcnt(6)
	v_mfma_f32_32x32x16_bf16 v[0:15], v[68:71], v[208:211], v[0:15]
	ds_read_b64_tr_b16 v[208:209], v199 offset:0x2200
	ds_read_b64_tr_b16 v[210:211], v199 offset:0x2300
	ds_read_b64_tr_b16 v[226:227], v199 offset:0x3200
	ds_read_b64_tr_b16 v[228:229], v199 offset:0x3300
	s_waitcnt lgkmcnt(8)
	v_mfma_f32_32x32x16_bf16 v[0:15], v[76:79], v[222:225], v[0:15]
	s_waitcnt lgkmcnt(6)
	v_mfma_f32_32x32x16_bf16 v[48:63], v[64:67], v[200:203], v[48:63]
	v_max3_f32 v212, v212, v80, v81
	v_max3_f32 v200, v212, v82, v83
	ds_read_b64_tr_b16 v[202:203], v199 offset:0x400
	v_max3_f32 v200, v200, v84, v85
	v_max3_f32 v200, v200, v86, v87
	v_max3_f32 v200, v200, v88, v89
	v_max3_f32 v200, v200, v90, v91
	s_waitcnt lgkmcnt(5)
	v_mfma_f32_32x32x16_bf16 v[48:63], v[72:75], v[204:207], v[48:63]
	ds_read_b64_tr_b16 v[204:205], v199 offset:0x500
	ds_read_b64_tr_b16 v[206:207], v199 offset:0x1400
	v_max3_f32 v200, v200, v92, v93
	v_max3_f32 v200, v200, v94, v95
	s_waitcnt lgkmcnt(5)
	v_mfma_f32_32x32x16_bf16 v[48:63], v[68:71], v[208:211], v[48:63]
	ds_read_b64_tr_b16 v[208:209], v199 offset:0x1500
	ds_read_b64_tr_b16 v[210:211], v199 offset:0x2400
	ds_read_b64_tr_b16 v[212:213], v199 offset:0x2500
	ds_read_b64_tr_b16 v[222:223], v199 offset:0x3400
	ds_read_b64_tr_b16 v[224:225], v199 offset:0x3500
	s_waitcnt lgkmcnt(8)
	v_mfma_f32_32x32x16_bf16 v[48:63], v[76:79], v[226:229], v[48:63]
	s_waitcnt lgkmcnt(6)
	v_mfma_f32_32x32x16_bf16 v[32:47], v[64:67], v[202:205], v[32:47]
	v_cmp_ge_f32_e32 vcc, s63, v200
	s_cmp_eq_u64 vcc, exec
	s_waitcnt lgkmcnt(4)
	v_mfma_f32_32x32x16_bf16 v[32:47], v[72:75], v[206:209], v[32:47]
	s_waitcnt lgkmcnt(2)
	v_mfma_f32_32x32x16_bf16 v[32:47], v[68:71], v[210:213], v[32:47]
	s_waitcnt lgkmcnt(0)
	v_mfma_f32_32x32x16_bf16 v[32:47], v[76:79], v[222:225], v[32:47]
	s_cbranch_scc0 .LBB0_438
	v_mov_b32_e32 v200, 1.0
	s_mov_b64 s[100:101], 0

.LBB0_429:
	v_exp_f32_e32 v199, v96
	v_exp_f32_e32 v221, v97
	v_exp_f32_e32 v226, v98
	v_exp_f32_e32 v227, v99
	v_exp_f32_e32 v228, v100
	v_exp_f32_e32 v229, v101
	v_exp_f32_e32 v230, v102
	v_exp_f32_e32 v231, v103
	v_exp_f32_e32 v232, v104
	v_exp_f32_e32 v233, v105
	v_exp_f32_e32 v234, v106
	v_exp_f32_e32 v235, v107
	v_exp_f32_e32 v236, v108
	v_exp_f32_e32 v237, v109
	v_exp_f32_e32 v238, v110
	v_exp_f32_e32 v239, v111
	v_xor_b32_e32 v64, 0x80000000, v195
	v_mov_b32_e32 v65, v64
	v_mov_b64_e32 v[66:67], v[64:65]
	v_mov_b64_e32 v[68:69], v[64:65]
	v_mov_b64_e32 v[70:71], v[64:65]
	v_mov_b64_e32 v[72:73], v[64:65]
	v_mov_b64_e32 v[74:75], v[64:65]
	v_mov_b64_e32 v[76:77], v[64:65]
	v_mov_b64_e32 v[78:79], v[64:65]
	s_waitcnt lgkmcnt(0)
	s_barrier
	v_add_u32_e32 v96, s17, v185
	ds_read_b128 v[202:205], v96 offset:49152
	ds_read_b128 v[206:209], v96 offset:57344
	v_add_u32_e32 v201, s17, v189
	v_exp_f32_e32 v80, v80
	s_waitcnt lgkmcnt(1)
	v_mfma_f32_32x32x16_bf16 v[96:111], v[202:205], v[124:127], v[64:79]
	v_exp_f32_e32 v81, v81
	v_exp_f32_e32 v82, v82
	v_exp_f32_e32 v83, v83
	v_exp_f32_e32 v84, v84
	v_exp_f32_e32 v85, v85
	v_exp_f32_e32 v86, v86
	v_exp_f32_e32 v87, v87
	s_waitcnt lgkmcnt(0)
	v_mfma_f32_32x32x16_bf16 v[64:79], v[206:209], v[124:127], v[64:79]
	ds_read_b128 v[202:205], v201 offset:49152
	ds_read_b128 v[206:209], v201 offset:57344
	v_add_u32_e32 v201, s17, v192
	v_exp_f32_e32 v240, v91
	v_exp_f32_e32 v241, v92
	v_cvt_pk_bf16_f32 v91, v230, v231
	v_cvt_pk_bf16_f32 v92, v232, v233
	s_waitcnt lgkmcnt(1)
	v_mfma_f32_32x32x16_bf16 v[96:111], v[202:205], v[120:123], v[96:111]
	ds_read_b128 v[202:205], v201 offset:49152
	ds_read_b128 v[210:213], v201 offset:57344
	v_add_u32_e32 v201, s17, v194
	s_waitcnt lgkmcnt(1)
	v_mfma_f32_32x32x16_bf16 v[96:111], v[202:205], v[116:119], v[96:111]
	v_exp_f32_e32 v203, v88
	v_add_f32_e32 v88, v221, v199
	v_add_f32_e32 v88, v226, v88
	v_add_f32_e32 v88, v227, v88
	v_add_f32_e32 v88, v228, v88
	v_add_f32_e32 v88, v229, v88
	v_add_f32_e32 v88, v230, v88
	v_add_f32_e32 v88, v231, v88
	v_add_f32_e32 v88, v232, v88
	v_add_f32_e32 v88, v233, v88
	v_mfma_f32_32x32x16_bf16 v[64:79], v[206:209], v[120:123], v[64:79]
	v_add_f32_e32 v88, v234, v88
	v_add_f32_e32 v88, v235, v88
	v_add_f32_e32 v88, v236, v88
	v_add_f32_e32 v88, v237, v88
	v_add_f32_e32 v88, v238, v88
	v_add_f32_e32 v88, v239, v88
	v_add_f32_e32 v88, v80, v88
	v_add_f32_e32 v88, v81, v88
	s_waitcnt lgkmcnt(0)
	v_mfma_f32_32x32x16_bf16 v[64:79], v[210:213], v[116:119], v[64:79]
	v_add_f32_e32 v88, v82, v88
	v_add_f32_e32 v88, v83, v88
	v_add_f32_e32 v88, v84, v88
	ds_read_b128 v[206:209], v201 offset:49152
	ds_read_b128 v[222:225], v201 offset:57344
	v_exp_f32_e32 v204, v89
	v_add_f32_e32 v88, v85, v88
	v_exp_f32_e32 v205, v90
	v_add_f32_e32 v88, v86, v88
	v_add_f32_e32 v88, v87, v88
	v_add_f32_e32 v88, v203, v88
	v_exp_f32_e32 v210, v93
	v_add_f32_e32 v88, v204, v88
	v_exp_f32_e32 v211, v94
	s_waitcnt lgkmcnt(1)
	v_mfma_f32_32x32x16_bf16 v[96:111], v[206:209], v[112:115], v[96:111]
	v_add_f32_e32 v88, v205, v88
	v_exp_f32_e32 v212, v95
	v_add_f32_e32 v88, v240, v88
	v_add_f32_e32 v88, v241, v88
	v_add_f32_e32 v88, v210, v88
	v_add_f32_e32 v88, v211, v88
	v_add_f32_e32 v201, v212, v88
	s_waitcnt lgkmcnt(0)
	v_mfma_f32_32x32x16_bf16 v[64:79], v[222:225], v[112:115], v[64:79]
	v_cvt_pk_bf16_f32 v88, v199, v221
	v_cvt_pk_bf16_f32 v89, v226, v227
	v_cvt_pk_bf16_f32 v90, v228, v229
	v_cvt_pk_bf16_f32 v93, v234, v235
	v_cvt_pk_bf16_f32 v94, v236, v237
	v_cvt_pk_bf16_f32 v95, v238, v239
	v_cvt_pk_bf16_f32 v80, v80, v81
	v_cvt_pk_bf16_f32 v81, v82, v83
	v_cvt_pk_bf16_f32 v82, v84, v85
	v_cvt_pk_bf16_f32 v83, v86, v87
	v_cvt_pk_bf16_f32 v84, v203, v204
	v_cvt_pk_bf16_f32 v85, v205, v240
	v_cvt_pk_bf16_f32 v86, v241, v210
	v_cvt_pk_bf16_f32 v87, v211, v212
	s_cmpk_gt_u32 s6, 0x7c
	s_cselect_b64 s[4:5], -1, 0
	s_and_b64 vcc, exec, s[4:5]
	s_cbranch_vccnz .Lattn_a0_lastw
	global_load_dwordx4 v[132:135], v244, s[98:99]
	global_load_dwordx4 v[128:131], v242, s[98:99]
	global_load_dwordx4 v[140:143], v245, s[98:99]
	global_load_dwordx4 v[136:139], v243, s[98:99]
	s_add_u32 s98, s98, 0x10000
	s_addc_u32 s99, s99, 0

.LBB0_436:
	v_exp_f32_e32 v152, v96
	v_exp_f32_e32 v153, v97
	v_exp_f32_e32 v154, v98
	v_exp_f32_e32 v155, v99
	v_exp_f32_e32 v156, v100
	v_exp_f32_e32 v157, v101
	v_exp_f32_e32 v158, v102
	v_exp_f32_e32 v159, v103
	v_exp_f32_e32 v144, v104
	v_exp_f32_e32 v145, v105
	v_exp_f32_e32 v146, v106
	v_exp_f32_e32 v147, v107
	v_exp_f32_e32 v148, v108
	v_exp_f32_e32 v149, v109
	v_exp_f32_e32 v150, v110
	v_exp_f32_e32 v151, v111
	v_fma_f32 v198, v196, v180, v197
	v_fma_f32 v180, v198, v200, v201
	v_xor_b32_e32 v80, 0x80000000, v195
	v_mov_b32_e32 v81, v80
	v_mov_b64_e32 v[82:83], v[80:81]
	v_mov_b64_e32 v[84:85], v[80:81]
	v_mov_b64_e32 v[86:87], v[80:81]
	v_mov_b64_e32 v[88:89], v[80:81]
	v_mov_b64_e32 v[90:91], v[80:81]
	v_mov_b64_e32 v[92:93], v[80:81]
	v_mov_b64_e32 v[94:95], v[80:81]
	s_add_i32 s6, s6, 2
	s_and_b64 vcc, exec, s[4:5]
	s_waitcnt lgkmcnt(0)
	s_barrier
	s_cbranch_vccnz .LBB0_440
	v_mov_b32_e32 v196, v199
	s_branch .LBB0_423

.LBB0_805:
	s_lshl_b32 s0, s39, 10
	s_and_b32 s6, s0, 0x800000
	s_lshl_b32 s0, s43, 1
	s_and_b32 s65, s0, 0x300
	s_lshl_b32 s0, s2, 11
	s_lshl_b32 s1, s2, 4
	s_and_b32 s0, s0, 0x2000
	s_and_b32 s1, s1, 0xffffff80
	s_add_i32 s1, s0, s1
	v_or_b32_e32 v171, s1, v170
	v_or_b32_e32 v0, v171, v169
	v_ashrrev_i32_e32 v1, 31, v0
	s_lshl_b32 s1, s2, 7
	v_lshlrev_b64 v[0:1], 10, v[0:1]
	s_and_b32 s64, s1, 0x180
	v_lshl_add_u64 v[0:1], s[86:87], 0, v[0:1]
	s_lshl_b32 s4, s64, 1
	s_mov_b32 s5, s7
	v_lshl_add_u64 v[0:1], v[0:1], 0, s[4:5]
	s_lshl_b32 s5, s0, 10
	s_add_u32 s0, s33, s5
	s_addc_u32 s1, s34, 0
	s_add_u32 s0, s0, s4
	v_mov_b32_e32 v174, v168
	v_lshl_add_u64 v[0:1], v[160:161], 1, v[0:1]
	s_addc_u32 s1, s1, 0
	v_lshl_add_u64 v[0:1], v[0:1], 0, v[162:163]
	v_ashrrev_i32_e32 v16, 4, v174
	s_add_u32 s5, s35, s5
	v_lshlrev_b32_e32 v20, 3, v174
	v_add_u32_e32 v18, 32, v16
	s_addc_u32 s16, s38, 0
	global_load_dwordx4 v[124:127], v[0:1], off
	global_load_dwordx4 v[120:123], v[0:1], off offset:32
	global_load_dwordx4 v[116:119], v[0:1], off offset:64
	global_load_dwordx4 v[112:115], v[0:1], off offset:96
	v_and_b32_e32 v0, 0x78, v20
	v_ashrrev_i32_e32 v17, 31, v16
	v_ashrrev_i32_e32 v19, 31, v18
	s_add_u32 s4, s5, s4
	v_lshlrev_b32_e32 v21, 1, v0
	v_lshlrev_b64 v[48:49], 10, v[16:17]
	v_lshlrev_b64 v[12:13], 10, v[18:19]
	s_addc_u32 s5, s16, 0
	v_or_b32_e32 v50, v48, v21
	v_mov_b32_e32 v51, v49
	v_or_b32_e32 v12, v12, v21
	v_lshl_add_u64 v[0:1], s[4:5], 0, v[50:51]
	v_lshl_add_u64 v[4:5], s[4:5], 0, v[12:13]
	s_barrier
	global_load_dwordx4 v[0:3], v[0:1], off
	s_nop 0
	global_load_dwordx4 v[4:7], v[4:5], off
	v_lshl_add_u64 v[8:9], s[0:1], 0, v[50:51]
	global_load_dwordx4 v[8:11], v[8:9], off
	v_lshl_add_u64 v[12:13], s[0:1], 0, v[12:13]
	global_load_dwordx4 v[12:15], v[12:13], off
	v_and_b32_e32 v22, 0xfffff0, v16
	v_lshlrev_b32_e32 v23, 1, v16
	v_lshrrev_b32_e32 v24, 1, v16
	v_and_b32_e32 v25, 3, v16
	v_and_or_b32 v22, v23, 8, v22
	v_and_or_b32 v23, v24, 4, v25
	v_and_b32_e32 v24, 0xfffff0, v18
	v_lshlrev_b32_e32 v25, 1, v18
	v_and_b32_e32 v17, 0x70, v174
	v_bfe_u32 v20, v20, 5, 2
	v_lshlrev_b32_e32 v16, 8, v16
	v_lshrrev_b32_e32 v22, 1, v22
	v_and_or_b32 v24, v25, 8, v24
	v_bitop3_b32 v183, v21, v16, v17 bitop3:0xde
	v_or_b32_e32 v16, v22, v20
	v_lshrrev_b32_e32 v22, 1, v24
	v_lshlrev_b32_e32 v23, 6, v23
	v_and_b32_e32 v26, 48, v21
	v_lshlrev_b32_e32 v16, 9, v16
	v_or_b32_e32 v20, v22, v20
	v_or3_b32 v184, v16, v23, v26
	v_lshlrev_b32_e32 v16, 9, v20
	v_bfe_u32 v172, v174, 5, 1
	v_ashrrev_i32_e32 v175, 8, v174
	v_lshlrev_b32_e32 v52, 4, v174
	v_or3_b32 v186, v16, v23, v26
	v_add_u32_e32 v84, 16, v184
	v_and_b32_e32 v173, 31, v174
	v_lshlrev_b32_e32 v19, 7, v175
	v_add_u32_e32 v24, 16, v183
	v_add_u32_e32 v85, 16, v186
	s_waitcnt vmcnt(0)
	v_lshlrev_b32_e32 v176, 4, v172
	v_lshlrev_b32_e32 v190, 8, v173
	v_and_b32_e32 v86, 63, v174
	v_lshl_add_u64 v[60:61], v[50:51], 0, s[14:15]
	v_lshl_add_u64 v[64:65], v[50:51], 0, s[36:37]
	v_lshl_add_u64 v[56:57], s[4:5], 0, v[64:65]
	v_lshl_add_u64 v[64:65], s[0:1], 0, v[64:65]
	s_cmp_lg_u32 16, -1
	s_cselect_b32 s16, 16, 0
	s_mov_b32 s17, s7
	s_mov_b32 s18, s7
	s_mov_b32 s19, s7
	s_mov_b32 s20, s7
	s_waitcnt vmcnt(3)
	ds_write_b128 v84, v[0:3]
	s_waitcnt vmcnt(2)
	ds_write_b128 v85, v[4:7]
	s_waitcnt vmcnt(1)
	ds_write_b128 v24, v[8:11] offset:49152
	v_and_b32_e32 v8, 0x70, v52
	v_lshlrev_b32_e32 v0, 8, v18
	v_bitop3_b32 v182, v176, v8, v19 bitop3:0x36
	v_bitop3_b32 v188, v21, v0, v17 bitop3:0xde
	v_add_u32_e32 v185, v182, v190
	v_add_u32_e32 v0, 16, v188
	v_add_u32_e32 v4, 16, v185
	s_waitcnt vmcnt(0)
	ds_write_b128 v0, v[12:15] offset:49152
	s_waitcnt lgkmcnt(0)
	s_barrier
	ds_read_b128 v[0:3], v4 offset:49152
	ds_read_b128 v[4:7], v4 offset:57344
	v_or_b32_e32 v9, v176, v19
	v_bitop3_b32 v187, v9, v8, 32 bitop3:0x36
	v_add_u32_e32 v189, v187, v190
	s_waitcnt lgkmcnt(0)
	v_mfma_f32_32x32x16_bf16 v[16:31], v[4:7], v[124:127], 0
	v_add_u32_e32 v4, 16, v189
	v_bitop3_b32 v193, v9, v8, s3 bitop3:0x36
	v_bitop3_b32 v191, v9, v8, 64 bitop3:0x36
	v_add_u32_e32 v194, v193, v190
	v_add_u32_e32 v192, v191, v190
	v_add_u32_e32 v8, 16, v194
	v_and_b32_e32 v5, 0x3fffffc0, v174
	v_mfma_f32_32x32x16_bf16 v[32:47], v[0:3], v[124:127], 0
	ds_read_b128 v[0:3], v4 offset:49152
	v_and_b32_e32 v11, 0xc0, v52
	v_add_u32_e32 v13, 16, v192
	ds_read_b128 v[52:55], v8 offset:57344
	v_lshl_add_u32 v177, v5, 2, s50
	ds_read_b128 v[4:7], v4 offset:57344
	v_lshlrev_b32_e32 v10, 3, v86
	s_waitcnt lgkmcnt(2)
	v_mfma_f32_32x32x16_bf16 v[32:47], v[0:3], v[120:123], v[32:47]
	v_lshlrev_b32_e32 v0, 1, v174
	v_and_b32_e32 v12, 32, v0
	ds_read_b128 v[0:3], v13 offset:49152
	v_and_or_b32 v11, v10, 24, v11
	s_mov_b32 s21, s7
	s_mov_b32 s22, s7
	s_mov_b32 s23, s7
	s_waitcnt lgkmcnt(0)
	v_mfma_f32_32x32x16_bf16 v[32:47], v[0:3], v[116:119], v[32:47]
	ds_read_b128 v[0:3], v8 offset:49152
	s_mov_b32 s24, s7
	s_mov_b32 s25, s7
	s_mov_b32 s26, s7
	s_mov_b32 s27, s7
	s_mov_b32 s28, s7
	s_mov_b32 s29, s7
	v_mfma_f32_32x32x16_bf16 v[16:31], v[4:7], v[120:123], v[16:31]
	v_and_b32_e32 v4, 0x100, v10
	v_lshlrev_b32_e32 v4, 3, v4
	v_or3_b32 v178, v11, v12, v4
	ds_read_b128 v[4:7], v13 offset:57344
	v_add_u32_e32 v181, s16, v178
	s_mov_b32 s16, s7
	s_mov_b32 s30, s7
	s_mov_b32 s31, s7
	s_waitcnt lgkmcnt(0)
	v_mfma_f32_32x32x16_bf16 v[16:31], v[4:7], v[116:119], v[16:31]
	v_lshl_add_u32 v179, v173, 2, v177
	v_mov_b32_e32 v196, 1.0
	v_mov_b32_e32 v180, 0
	v_mfma_f32_32x32x16_bf16 v[32:47], v[0:3], v[112:115], v[32:47]
	v_mov_b64_e32 v[0:1], s[16:17]
	v_mov_b64_e32 v[14:15], s[30:31]
	v_mov_b64_e32 v[2:3], s[18:19]
	v_mov_b64_e32 v[4:5], s[20:21]
	v_mov_b64_e32 v[6:7], s[22:23]
	v_mov_b64_e32 v[8:9], s[24:25]
	v_mov_b64_e32 v[10:11], s[26:27]
	v_mfma_f32_32x32x16_bf16 v[16:31], v[52:55], v[112:115], v[16:31]
	s_nop 3
	v_max_f32_e32 v52, v33, v33
	v_max_f32_e32 v53, v32, v32
	v_max_f32_e32 v52, v53, v52
	v_max3_f32 v52, v52, v34, v35
	v_max3_f32 v52, v52, v36, v37
	v_max3_f32 v52, v52, v38, v39
	v_max3_f32 v52, v52, v40, v41
	v_max3_f32 v52, v52, v42, v43
	v_max3_f32 v52, v52, v44, v45
	v_max3_f32 v66, v52, v46, v47
	v_lshl_add_u64 v[52:53], s[4:5], 0, v[60:61]
	v_lshl_add_u64 v[60:61], s[0:1], 0, v[60:61]
	global_load_dwordx4 v[52:55], v[52:53], off
	s_nop 0
	global_load_dwordx4 v[56:59], v[56:57], off
	v_mov_b64_e32 v[12:13], s[28:29]
	global_load_dwordx4 v[60:63], v[60:61], off
	s_mov_b32 s19, 1
	global_load_dwordx4 v[80:83], v[64:65], off
	v_max3_f32 v64, v66, v16, v17
	v_max3_f32 v64, v64, v18, v19
	v_max3_f32 v64, v64, v20, v21
	v_max3_f32 v64, v64, v22, v23
	v_max3_f32 v64, v64, v24, v25
	v_max3_f32 v64, v64, v26, v27
	v_max3_f32 v64, v64, v28, v29
	v_max3_f32 v70, v64, v30, v31
	v_lshl_add_u64 v[64:65], v[50:51], 0, s[40:41]
	v_lshl_add_u64 v[66:67], s[0:1], 0, v[64:65]
	v_lshl_add_u64 v[50:51], v[50:51], 0, s[44:45]
	v_lshl_add_u64 v[64:65], s[4:5], 0, v[64:65]
	v_lshl_add_u64 v[68:69], s[0:1], 0, v[50:51]
	global_load_dwordx4 v[136:139], v[66:67], off
	global_load_dwordx4 v[128:131], v[68:69], off
	v_lshl_add_u64 v[50:51], s[4:5], 0, v[50:51]
	global_load_dwordx4 v[140:143], v[64:65], off
	global_load_dwordx4 v[132:135], v[50:51], off
	v_mov_b32_e32 v71, v70
	s_nop 1
	v_permlane32_swap_b32_e32 v70, v71
	v_max_f32_e32 v50, v71, v71
	v_max_f32_e32 v51, v70, v70
	v_max_f32_e32 v50, v51, v50
	v_sub_f32_e32 v64, v16, v50
	v_add_u32_e32 v16, s58, v183
	v_sub_f32_e32 v32, v32, v50
	v_sub_f32_e32 v33, v33, v50
	v_sub_f32_e32 v34, v34, v50
	v_sub_f32_e32 v35, v35, v50
	v_sub_f32_e32 v36, v36, v50
	v_sub_f32_e32 v37, v37, v50
	v_sub_f32_e32 v38, v38, v50
	v_sub_f32_e32 v39, v39, v50
	v_sub_f32_e32 v40, v40, v50
	v_sub_f32_e32 v41, v41, v50
	v_sub_f32_e32 v42, v42, v50
	v_sub_f32_e32 v43, v43, v50
	v_sub_f32_e32 v44, v44, v50
	v_sub_f32_e32 v45, v45, v50
	v_sub_f32_e32 v46, v46, v50
	v_sub_f32_e32 v47, v47, v50
	v_sub_f32_e32 v66, v18, v50
	s_waitcnt vmcnt(4)
	s_waitcnt vmcnt(7)
	ds_write_b128 v84, v[52:55] offset:16384
	s_waitcnt vmcnt(6)
	ds_write_b128 v85, v[56:59] offset:16384
	v_and_b32_e32 v18, 15, v174
	s_waitcnt vmcnt(5)
	ds_write_b128 v16, v[60:63]
	v_add_u32_e32 v16, s58, v188
	v_sub_f32_e32 v65, v17, v50
	v_exp_f32_e32 v152, v32
	v_exp_f32_e32 v153, v33
	v_exp_f32_e32 v154, v34
	v_exp_f32_e32 v155, v35
	v_exp_f32_e32 v156, v36
	v_exp_f32_e32 v157, v37
	v_exp_f32_e32 v158, v38
	v_exp_f32_e32 v159, v39
	v_exp_f32_e32 v144, v40
	v_exp_f32_e32 v145, v41
	v_exp_f32_e32 v146, v42
	v_exp_f32_e32 v147, v43
	v_exp_f32_e32 v148, v44
	v_exp_f32_e32 v149, v45
	v_exp_f32_e32 v150, v46
	v_exp_f32_e32 v151, v47
	s_waitcnt vmcnt(4)
	ds_write_b128 v16, v[80:83]
	v_lshl_add_u64 v[16:17], s[6:7], 0, v[48:49]
	v_lshlrev_b32_e32 v18, 4, v18
	v_or3_b32 v16, v16, s65, v18
	v_add_f32_e32 v195, 0, v50
	v_sub_f32_e32 v79, v31, v50
	v_sub_f32_e32 v78, v30, v50
	v_sub_f32_e32 v77, v29, v50
	v_sub_f32_e32 v76, v28, v50
	v_sub_f32_e32 v75, v27, v50
	v_sub_f32_e32 v74, v26, v50
	v_sub_f32_e32 v73, v25, v50
	v_sub_f32_e32 v72, v24, v50
	v_sub_f32_e32 v71, v23, v50
	v_sub_f32_e32 v70, v22, v50
	v_sub_f32_e32 v69, v21, v50
	v_sub_f32_e32 v68, v20, v50
	v_sub_f32_e32 v67, v19, v50
	v_lshl_add_u64 v[166:167], s[12:13], 0, v[16:17]
	v_mov_b64_e32 v[62:63], v[14:15]
	v_mov_b64_e32 v[46:47], v[14:15]
	v_mov_b64_e32 v[30:31], v[14:15]
	v_cmp_gt_u32_e64 s[0:1], 32, v86
	v_mov_b64_e32 v[60:61], v[12:13]
	v_mov_b64_e32 v[58:59], v[10:11]
	v_mov_b64_e32 v[56:57], v[8:9]
	v_mov_b64_e32 v[54:55], v[6:7]
	v_mov_b64_e32 v[52:53], v[4:5]
	v_mov_b64_e32 v[50:51], v[2:3]
	v_mov_b64_e32 v[48:49], v[0:1]
	v_mov_b64_e32 v[44:45], v[12:13]
	v_mov_b64_e32 v[42:43], v[10:11]
	v_mov_b64_e32 v[40:41], v[8:9]
	v_mov_b64_e32 v[38:39], v[6:7]
	v_mov_b64_e32 v[36:37], v[4:5]
	v_mov_b64_e32 v[34:35], v[2:3]
	v_mov_b64_e32 v[32:33], v[0:1]
	v_mov_b64_e32 v[28:29], v[12:13]
	v_mov_b64_e32 v[26:27], v[10:11]
	v_mov_b64_e32 v[24:25], v[8:9]
	v_mov_b64_e32 v[22:23], v[6:7]
	v_mov_b64_e32 v[20:21], v[4:5]
	v_mov_b64_e32 v[18:19], v[2:3]
	v_mov_b64_e32 v[16:17], v[0:1]
	s_mov_b32 s6, 1
	s_mov_b32 s18, 0
	s_waitcnt lgkmcnt(0)
	s_barrier
	v_add_co_u32_e32 v242, vcc, s61, v166
	s_nop 1
	v_addc_co_u32_e32 v243, vcc, -1, v167, vcc
	s_nop 0
	v_readfirstlane_b32 s98, v242
	v_readfirstlane_b32 s99, v243
	s_nop 1
	v_subrev_u32_e32 v242, s98, v242
	v_add_u32_e32 v243, 0x8000, v242
	v_add_u32_e32 v244, 0x1000000, v242
	v_add_u32_e32 v245, 0x1008000, v242
	v_xor_b32_e32 v80, 0x80000000, v195
	v_mov_b32_e32 v81, v80
	v_mov_b64_e32 v[82:83], v[80:81]
	v_mov_b64_e32 v[84:85], v[80:81]
	v_mov_b64_e32 v[86:87], v[80:81]
	v_mov_b64_e32 v[88:89], v[80:81]
	v_mov_b64_e32 v[90:91], v[80:81]
	v_mov_b64_e32 v[92:93], v[80:81]
	v_mov_b64_e32 v[94:95], v[80:81]
